# GEMM tile prologues: dropped the compiler-added vmcnt(0) after the counted vmcnt(12), so the first k-step starts once stage 0 has landed
# speedup vs baseline: 1.0066x; 1.0019x over previous
; template <bool IN_PROJ>
; DI void gemm_tile(const Params& p, int layer, int nt, int tt, char* smem) {
;     ...
;   const __amdgpu_buffer_rsrc_t rA = __builtin_amdgcn_make_buffer_rsrc((void*)(Wt + (size_t)n0 * DM), 0, 0x7fffffff, 0x00020000);
;   const __amdgpu_buffer_rsrc_t rB0 = __builtin_amdgcn_make_buffer_rsrc((void*)(IN_PROJ ? xb + (size_t)t0 * DM : mixA + (size_t)t0 * 512), 0, 0x7fffffff, 0x00020000);
;   const __amdgpu_buffer_rsrc_t rB1 = __builtin_amdgcn_make_buffer_rsrc((void*)(mixB + (size_t)t0 * 256), 0, 0x7fffffff, 0x00020000);
;   const __amdgpu_buffer_rsrc_t rB2 = __builtin_amdgcn_make_buffer_rsrc((void*)(mixC + (size_t)t0 * 256), 0, 0x7fffffff, 0x00020000);
;   int voA[4], rowB[2], lcB[2];
; #pragma unroll
;   for (int i = 0; i < 4; ++i) { int c = tid + 256 * i; int row = c >> 2, lc = (c & 3) ^ ((row >> 2) & 3); voA[i] = row * (DM * 2) + lc * 16; }
; #pragma unroll
;   for (int i = 0; i < 2; ++i) { int c = tid + 256 * i; rowB[i] = c >> 2; lcB[i] = ((c & 3) ^ ((rowB[i] >> 2) & 3)) * 16; }
;   auto stage = [&](int kt) {
;     const int k0 = kt * 32;
;     char* base = smem + (kt % 3) * G_STAGE + w * 1024;
; #pragma unroll
;     for (int i = 0; i < 4; ++i)
;       __builtin_amdgcn_raw_ptr_buffer_load_lds(rA, (lds_ptr_t)(base + i * 4096), 16, voA[i], k0 * 2, 0, 0);
; #pragma unroll
;     for (int i = 0; i < 2; ++i) {
;       lds_ptr_t dst = (lds_ptr_t)(base + 16384 + i * 4096);
;       if (IN_PROJ) __builtin_amdgcn_raw_ptr_buffer_load_lds(rB0, dst, 16, rowB[i] * (DM * 2) + lcB[i], k0 * 2, 0, 0);
;       else {
;         if (k0 < 512) __builtin_amdgcn_raw_ptr_buffer_load_lds(rB0, dst, 16, rowB[i] * 1024 + lcB[i], k0 * 2, 0, 0);
;         else if (k0 < 768) __builtin_amdgcn_raw_ptr_buffer_load_lds(rB1, dst, 16, rowB[i] * 512 + lcB[i], (k0 - 512) * 2, 0, 0);
;         else __builtin_amdgcn_raw_ptr_buffer_load_lds(rB2, dst, 16, rowB[i] * 512 + lcB[i], (k0 - 768) * 2, 0, 0);
;       }
;     }
;   };
;   asm volatile("s_waitcnt vmcnt(0)" ::: "memory");
;   __syncthreads();
;   stage(0); stage(1); stage(2);
; template <bool IN_PROJ>
; DI void gemm_phase(const Params& p, int layer, char* smem) {
;     ...
;       __syncthreads();
;       if (tidx(p) == 0) *s_tile = (int)atomicAdd(ctr + xq, 1u);
;       __syncthreads();
;       const int q = __builtin_amdgcn_readfirstlane(*s_tile);
;       if (q >= PER_XCD) break;
;       int grp = q / (8 * NT), rem = q % (8 * NT);
.LBB0_70:
	s_or_b64 exec, exec, s[0:1]
	s_waitcnt lgkmcnt(0)
	s_barrier
	ds_read_b32 v0, v242
	s_mov_b64 s[0:1], -1
	s_waitcnt lgkmcnt(0)
	v_readfirstlane_b32 s2, v0
	s_cmpk_gt_i32 s2, 0x32f
	s_cbranch_scc1 .LBB0_65
	s_mul_hi_i32 s0, s2, 0x78787879
	s_lshr_b32 s1, s0, 31
	s_ashr_i32 s0, s0, 6
	s_add_i32 s1, s0, s1
	s_mul_i32 s0, s1, 0x88
	s_sub_i32 s2, s2, s0
	s_ashr_i32 s82, s2, 3
	s_lshl_b32 s2, s2, 3
	s_lshl_b32 s1, s1, 6
	s_and_b32 s2, s2, 56
	v_mov_b32_e32 v0, v234
	s_or_b32 s1, s2, s1
	s_lshl_b32 s94, s82, 8
	v_add_u32_e32 v247, s33, v0
	s_or_b32 s72, s1, s81
	s_ashr_i32 s95, s94, 31
	v_readfirstlane_b32 s60, v247
	s_ashr_i32 s1, s60, 6
	s_ashr_i32 s75, s60, 7
	s_lshl_b32 s92, s72, 7
	s_lshl_b64 s[2:3], s[94:95], 11
	s_add_u32 s4, s67, s2
	s_addc_u32 s5, s80, s3
	s_ashr_i32 s93, s92, 31
	s_lshl_b64 s[2:3], s[92:93], 11
	s_add_u32 s8, s48, s2
	v_lshlrev_b32_e32 v2, 4, v247
	s_addc_u32 s2, s49, s3
	v_lshlrev_b32_e32 v1, 9, v247
	v_bitop3_b32 v2, v2, 48, v247 bitop3:0x48
	s_and_b32 s3, s1, 1
	s_lshl_b32 s1, s1, 10
	v_and_or_b32 v181, v1, s86, v2
	s_and_b32 s5, s5, 0xffff
	s_mov_b32 m0, s1
	v_add_u32_e32 v182, 0x20000, v181
	s_waitcnt vmcnt(0)
	s_barrier
	buffer_load_dwordx4 v181, s[4:7], 0 offen lds
	s_add_i32 m0, s1, 0x1000
	v_add_u32_e32 v183, 0x40000, v181
	buffer_load_dwordx4 v182, s[4:7], 0 offen lds
	s_add_i32 m0, s1, 0x2000
	v_add_u32_e32 v184, 0x60000, v181
	v_add_u32_e32 v248, 0x100, v247
	buffer_load_dwordx4 v183, s[4:7], 0 offen lds
	s_add_i32 m0, s1, 0x3000
	s_and_b32 s9, s2, 0xffff
	s_mov_b32 s10, s6
	s_mov_b32 s11, s7
	buffer_load_dwordx4 v184, s[4:7], 0 offen lds
	s_add_i32 m0, s1, 0x4000
	v_lshlrev_b32_e32 v1, 9, v248
	buffer_load_dwordx4 v181, s[8:11], 0 offen lds
	s_add_i32 m0, s1, 0x5000
	v_and_or_b32 v185, v1, s86, v2
	buffer_load_dwordx4 v185, s[8:11], 0 offen lds
	s_add_i32 m0, s1, 0x6000
	v_lshrrev_b32_e32 v0, 5, v247
	buffer_load_dwordx4 v181, s[4:7], 64 offen lds
	s_add_i32 m0, s1, 0x7000
	v_and_b32_e32 v199, 31, v247
	buffer_load_dwordx4 v182, s[4:7], 64 offen lds
	s_add_i32 m0, s1, 0x8000
	v_bfe_u32 v3, v247, 2, 2
	buffer_load_dwordx4 v183, s[4:7], 64 offen lds
	s_add_i32 m0, s1, 0x9000
	v_lshlrev_b32_e32 v1, 5, v199
	buffer_load_dwordx4 v184, s[4:7], 64 offen lds
	s_add_i32 m0, s1, 0xa000
	v_bitop3_b32 v0, v0, v3, 1 bitop3:0x6c
	buffer_load_dwordx4 v181, s[8:11], 64 offen lds
	s_add_i32 m0, s1, 0xb000
	s_and_b32 s2, s60, 0x7ffff80
	buffer_load_dwordx4 v185, s[8:11], 64 offen lds
	s_add_i32 m0, s1, 0xc000
	v_lshl_or_b32 v2, s75, 12, v1
	buffer_load_dwordx4 v181, s[4:7], s87 offen lds
	s_add_i32 m0, s1, 0xd000
	v_lshlrev_b32_e32 v0, 3, v0
	buffer_load_dwordx4 v182, s[4:7], s87 offen lds
	s_add_i32 m0, s1, 0xe000
	v_or_b32_e32 v4, s2, v199
	buffer_load_dwordx4 v183, s[4:7], s87 offen lds
	s_add_i32 m0, s1, 0xf000
	v_or_b32_e32 v189, v0, v2
	buffer_load_dwordx4 v184, s[4:7], s87 offen lds
	s_add_i32 m0, s1, 0x10000
	v_lshlrev_b32_e32 v4, 5, v4
	buffer_load_dwordx4 v181, s[8:11], s87 offen lds
	s_add_i32 m0, s1, 0x11000
	s_lshl_b32 s74, s3, 6
	buffer_load_dwordx4 v185, s[8:11], s87 offen lds
	v_lshlrev_b32_e32 v177, 1, v189
	v_or_b32_e32 v190, v4, v0
	v_lshl_or_b32 v1, s3, 11, v1
	v_or_b32_e32 v192, s74, v199
	v_readlane_b32 s98, v249, 10
	v_readlane_b32 s99, v249, 11
	v_or_b32_e32 v206, s92, v192
	v_ashrrev_i32_e32 v207, 31, v206
	v_lshl_add_u64 v[206:207], v[206:207], 2, s[98:99]
	global_load_dword v204, v[206:207], off
	global_load_dword v205, v[206:207], off offset:128
	s_waitcnt vmcnt(12)
	s_nop 0
	s_barrier
; #define MFMA32(a, b, c) __builtin_amdgcn_mfma_f32_32x32x16_bf16((a), (b), (c), 0, 0, 0)
; template <bool IN_PROJ>
; DI void gemm_tile(const Params& p, int layer, int nt, int tt, char* smem) {
;     ...
;   f32x16 acc[4][2];
; #pragma unroll
;   for (int a = 0; a < 4; ++a)
; #pragma unroll
;     for (int b = 0; b < 2; ++b)
; #pragma unroll
;       for (int i = 0; i < 16; ++i) acc[a][b][i] = 0.f;
;     ...
;   auto load_frags = [&](int kt, int ks, bf16x8 (&fa)[4], bf16x8 (&fb)[2]) {
;     const u16* sA = (const u16*)(smem + (kt % 3) * G_STAGE);
;     const u16* sB = sA + 8192;
; #pragma unroll
;     for (int fi = 0; fi < 4; ++fi) fa[fi] = *(const bf16x8*)(sA + gswz(wf * 128 + fi * 32 + r, ks * 2 + h));
; #pragma unroll
;     for (int ti = 0; ti < 2; ++ti) fb[ti] = *(const bf16x8*)(sB + gswz(wt * 64 + ti * 32 + r, ks * 2 + h));
;   };
;   auto mma = [&](const bf16x8 (&fa)[4], const bf16x8 (&fb)[2]) {
; #pragma unroll
;     for (int fi = 0; fi < 4; ++fi)
; #pragma unroll
;       for (int ti = 0; ti < 2; ++ti) acc[fi][ti] = MFMA32(fa[fi], fb[ti], acc[fi][ti]);
;   };
;   bf16x8 fa0[4], fb0[2], fa1[4], fb1[2];
;   asm volatile("s_waitcnt vmcnt(12)" ::: "memory");
;   __syncthreads();
;   load_frags(0, 0, fa0, fb0);
	v_lshlrev_b32_e32 v176, 1, v190
	ds_read_b128 v[132:135], v177
	ds_read_b128 v[104:107], v176 offset:2048
	ds_read_b128 v[100:103], v176 offset:4096
	ds_read_b128 v[96:99], v176 offset:6144
	v_or_b32_e32 v191, v1, v0
	v_lshlrev_b32_e32 v5, 5, v192
	v_lshlrev_b32_e32 v178, 1, v191
	v_or_b32_e32 v194, v5, v0
	v_lshlrev_b32_e32 v179, 1, v194
	ds_read_b128 v[128:131], v178 offset:16384
	ds_read_b128 v[108:111], v179 offset:18432
	v_bfe_u32 v198, v247, 5, 1
	v_bitop3_b32 v0, v198, v3, 2 bitop3:0x36
	v_lshlrev_b32_e32 v0, 3, v0
	v_mov_b32_e32 v64, 0
	s_mov_b32 s0, 3
	v_or_b32_e32 v188, v0, v2
	v_or_b32_e32 v187, v0, v1
	v_or_b32_e32 v186, v0, v4
	v_or_b32_e32 v180, v5, v0
	s_movk_i32 s2, 0xc0
	v_mov_b32_e32 v65, v64
	v_mov_b32_e32 v66, v64
	v_mov_b32_e32 v67, v64
	v_mov_b32_e32 v68, v64
	v_mov_b32_e32 v69, v64
	v_mov_b32_e32 v70, v64
	v_mov_b32_e32 v71, v64
	v_mov_b32_e32 v72, v64
	v_mov_b32_e32 v73, v64
	v_mov_b32_e32 v74, v64
	v_mov_b32_e32 v75, v64
	v_mov_b32_e32 v76, v64
	v_mov_b32_e32 v77, v64
	v_mov_b32_e32 v78, v64
	v_mov_b32_e32 v79, v64
	v_mov_b32_e32 v0, v64
	v_mov_b32_e32 v1, v64
	v_mov_b32_e32 v2, v64
	v_mov_b32_e32 v3, v64
	v_mov_b32_e32 v4, v64
	v_mov_b32_e32 v5, v64
	v_mov_b32_e32 v6, v64
	v_mov_b32_e32 v7, v64
	v_mov_b32_e32 v8, v64
	v_mov_b32_e32 v9, v64
	v_mov_b32_e32 v10, v64
	v_mov_b32_e32 v11, v64
	v_mov_b32_e32 v12, v64
	v_mov_b32_e32 v13, v64
	v_mov_b32_e32 v14, v64
	v_mov_b32_e32 v15, v64
	v_mov_b32_e32 v80, v64
	v_mov_b32_e32 v81, v64
	v_mov_b32_e32 v82, v64
	v_mov_b32_e32 v83, v64
	v_mov_b32_e32 v84, v64
	v_mov_b32_e32 v85, v64
	v_mov_b32_e32 v86, v64
	v_mov_b32_e32 v87, v64
	v_mov_b32_e32 v88, v64
	v_mov_b32_e32 v89, v64
	v_mov_b32_e32 v90, v64
	v_mov_b32_e32 v91, v64
	v_mov_b32_e32 v92, v64
	v_mov_b32_e32 v93, v64
	v_mov_b32_e32 v94, v64
	v_mov_b32_e32 v95, v64
	v_mov_b32_e32 v16, v64
	v_mov_b32_e32 v17, v64
	v_mov_b32_e32 v18, v64
	v_mov_b32_e32 v19, v64
	v_mov_b32_e32 v20, v64
	v_mov_b32_e32 v21, v64
	v_mov_b32_e32 v22, v64
	v_mov_b32_e32 v23, v64
	v_mov_b32_e32 v24, v64
	v_mov_b32_e32 v25, v64
	v_mov_b32_e32 v26, v64
	v_mov_b32_e32 v27, v64
	v_mov_b32_e32 v28, v64
	v_mov_b32_e32 v29, v64
	v_mov_b32_e32 v30, v64
	v_mov_b32_e32 v31, v64
	v_mov_b32_e32 v112, v64
	v_mov_b32_e32 v113, v64
	v_mov_b32_e32 v114, v64
	v_mov_b32_e32 v115, v64
	v_mov_b32_e32 v116, v64
	v_mov_b32_e32 v117, v64
	v_mov_b32_e32 v118, v64
	v_mov_b32_e32 v119, v64
	v_mov_b32_e32 v120, v64
	v_mov_b32_e32 v121, v64
	v_mov_b32_e32 v122, v64
	v_mov_b32_e32 v123, v64
	v_mov_b32_e32 v124, v64
	v_mov_b32_e32 v125, v64
	v_mov_b32_e32 v126, v64
	v_mov_b32_e32 v127, v64
	v_mov_b32_e32 v32, v64
	v_mov_b32_e32 v33, v64
	v_mov_b32_e32 v34, v64
	v_mov_b32_e32 v35, v64
	v_mov_b32_e32 v36, v64
	v_mov_b32_e32 v37, v64
	v_mov_b32_e32 v38, v64
	v_mov_b32_e32 v39, v64
	v_mov_b32_e32 v40, v64
	v_mov_b32_e32 v41, v64
	v_mov_b32_e32 v42, v64
	v_mov_b32_e32 v43, v64
	v_mov_b32_e32 v44, v64
	v_mov_b32_e32 v45, v64
	v_mov_b32_e32 v46, v64
	v_mov_b32_e32 v47, v64
	v_mov_b32_e32 v144, v64
	v_mov_b32_e32 v145, v64
	v_mov_b32_e32 v146, v64
	v_mov_b32_e32 v147, v64
	v_mov_b32_e32 v148, v64
	v_mov_b32_e32 v149, v64
	v_mov_b32_e32 v150, v64
	v_mov_b32_e32 v151, v64
	v_mov_b32_e32 v152, v64
	v_mov_b32_e32 v153, v64
	v_mov_b32_e32 v154, v64
	v_mov_b32_e32 v155, v64
	v_mov_b32_e32 v156, v64
	v_mov_b32_e32 v157, v64
	v_mov_b32_e32 v158, v64
	v_mov_b32_e32 v159, v64
	v_mov_b32_e32 v48, v64
	v_mov_b32_e32 v49, v64
	v_mov_b32_e32 v50, v64
	v_mov_b32_e32 v51, v64
	v_mov_b32_e32 v52, v64
	v_mov_b32_e32 v53, v64
	v_mov_b32_e32 v54, v64
	v_mov_b32_e32 v55, v64
	v_mov_b32_e32 v56, v64
	v_mov_b32_e32 v57, v64
	v_mov_b32_e32 v58, v64
	v_mov_b32_e32 v59, v64
	v_mov_b32_e32 v60, v64
	v_mov_b32_e32 v61, v64
	v_mov_b32_e32 v62, v64
	v_mov_b32_e32 v63, v64

; template <bool IN_PROJ>
; DI void gemm_tile(const Params& p, int layer, int nt, int tt, char* smem) {
;     ...
;   const __amdgpu_buffer_rsrc_t rA = __builtin_amdgcn_make_buffer_rsrc((void*)(Wt + (size_t)n0 * DM), 0, 0x7fffffff, 0x00020000);
;   const __amdgpu_buffer_rsrc_t rB0 = __builtin_amdgcn_make_buffer_rsrc((void*)(IN_PROJ ? xb + (size_t)t0 * DM : mixA + (size_t)t0 * 512), 0, 0x7fffffff, 0x00020000);
;   const __amdgpu_buffer_rsrc_t rB1 = __builtin_amdgcn_make_buffer_rsrc((void*)(mixB + (size_t)t0 * 256), 0, 0x7fffffff, 0x00020000);
;   const __amdgpu_buffer_rsrc_t rB2 = __builtin_amdgcn_make_buffer_rsrc((void*)(mixC + (size_t)t0 * 256), 0, 0x7fffffff, 0x00020000);
;   int voA[4], rowB[2], lcB[2];
; #pragma unroll
;   for (int i = 0; i < 4; ++i) { int c = tid + 256 * i; int row = c >> 2, lc = (c & 3) ^ ((row >> 2) & 3); voA[i] = row * (DM * 2) + lc * 16; }
; #pragma unroll
;   for (int i = 0; i < 2; ++i) { int c = tid + 256 * i; rowB[i] = c >> 2; lcB[i] = ((c & 3) ^ ((rowB[i] >> 2) & 3)) * 16; }
;   auto stage = [&](int kt) {
;     const int k0 = kt * 32;
;     char* base = smem + (kt % 3) * G_STAGE + w * 1024;
; #pragma unroll
;     for (int i = 0; i < 4; ++i)
;       __builtin_amdgcn_raw_ptr_buffer_load_lds(rA, (lds_ptr_t)(base + i * 4096), 16, voA[i], k0 * 2, 0, 0);
; #pragma unroll
;     for (int i = 0; i < 2; ++i) {
;       lds_ptr_t dst = (lds_ptr_t)(base + 16384 + i * 4096);
;       if (IN_PROJ) __builtin_amdgcn_raw_ptr_buffer_load_lds(rB0, dst, 16, rowB[i] * (DM * 2) + lcB[i], k0 * 2, 0, 0);
;       else {
;         if (k0 < 512) __builtin_amdgcn_raw_ptr_buffer_load_lds(rB0, dst, 16, rowB[i] * 1024 + lcB[i], k0 * 2, 0, 0);
;         else if (k0 < 768) __builtin_amdgcn_raw_ptr_buffer_load_lds(rB1, dst, 16, rowB[i] * 512 + lcB[i], (k0 - 512) * 2, 0, 0);
;         else __builtin_amdgcn_raw_ptr_buffer_load_lds(rB2, dst, 16, rowB[i] * 512 + lcB[i], (k0 - 768) * 2, 0, 0);
;       }
;     }
;   };
;   asm volatile("s_waitcnt vmcnt(0)" ::: "memory");
;   __syncthreads();
;   stage(0); stage(1); stage(2);
; template <bool IN_PROJ>
; DI void gemm_phase(const Params& p, int layer, char* smem) {
;     ...
;       __syncthreads();
;       if (tidx(p) == 0) *s_tile = (int)atomicAdd(ctr + xq, 1u);
;       __syncthreads();
;       const int q = __builtin_amdgcn_readfirstlane(*s_tile);
;       if (q >= PER_XCD) break;
;       int grp = q / (8 * NT), rem = q % (8 * NT);
.LBB0_728:
	s_or_b64 exec, exec, s[2:3]
	s_waitcnt lgkmcnt(0)
	s_barrier
	ds_read_b32 v0, v174
	s_mov_b64 s[2:3], -1
	s_waitcnt lgkmcnt(0)
	v_readfirstlane_b32 s4, v0
	s_cmpk_gt_i32 s4, 0xbf
	s_cbranch_scc1 .LBB0_723
	s_ashr_i32 s2, s4, 31
	s_lshr_b32 s2, s2, 27
	s_add_i32 s2, s4, s2
	s_and_b32 s3, s2, 0xffffffe0
	s_sub_i32 s3, s4, s3
	s_lshl_b32 s2, s2, 1
	s_lshl_b32 s4, s3, 3
	s_and_b32 s2, s2, 0x1ffffc0
	s_and_b32 s4, s4, 56
	v_mov_b32_e32 v0, v234
	s_lshl_b32 s3, s3, 5
	s_or_b32 s2, s4, s2
	s_and_b32 s20, s3, 0xffffff00
	v_add_u32_e32 v176, s33, v0
	s_or_b32 s2, s2, s37
	s_ashr_i32 s21, s20, 31
	v_readfirstlane_b32 s14, v176
	s_ashr_i32 s15, s14, 6
	s_ashr_i32 s38, s14, 7
	s_lshl_b32 s2, s2, 7
	s_lshl_b64 s[4:5], s[20:21], 11
	s_add_u32 s8, s29, s4
	s_addc_u32 s9, s30, s5
	s_ashr_i32 s3, s2, 31
	s_lshl_b64 s[4:5], s[2:3], 10
	s_add_u32 s4, s48, s4
	s_addc_u32 s5, s49, s5
	s_lshl_b64 s[10:11], s[2:3], 9
	s_add_u32 s12, s68, s10
	s_addc_u32 s3, s69, s11
	s_add_u32 s16, s50, s10
	v_lshlrev_b32_e32 v172, 4, v176
	s_addc_u32 s17, s51, s11
	v_lshlrev_b32_e32 v1, 9, v176
	v_bitop3_b32 v2, v172, 48, v176 bitop3:0x48
	s_and_b32 s13, s3, 0xffff
	s_lshl_b32 s3, s15, 10
	v_and_or_b32 v184, v1, s34, v2
	s_and_b32 s9, s9, 0xffff
	s_mov_b32 s10, s6
	s_mov_b32 s11, s7
	s_mov_b32 m0, s3
	v_add_u32_e32 v185, 0x20000, v184
	s_waitcnt vmcnt(0)
	s_barrier
	buffer_load_dwordx4 v184, s[8:11], 0 offen lds
	s_add_i32 m0, s3, 0x1000
	v_add_u32_e32 v186, 0x40000, v184
	buffer_load_dwordx4 v185, s[8:11], 0 offen lds
	s_add_i32 m0, s3, 0x2000
	v_add_u32_e32 v187, 0x60000, v184
	v_ashrrev_i32_e32 v3, 2, v176
	v_add_u32_e32 v177, 0x100, v176
	buffer_load_dwordx4 v186, s[8:11], 0 offen lds
	s_add_i32 m0, s3, 0x3000
	v_ashrrev_i32_e32 v4, 2, v177
	s_and_b32 s5, s5, 0xffff
	buffer_load_dwordx4 v187, s[8:11], 0 offen lds
	s_add_i32 m0, s3, 0x4000
	v_lshl_or_b32 v189, v3, 10, v2
	buffer_load_dwordx4 v189, s[4:7], 0 offen lds
	s_add_i32 m0, s3, 0x5000
	v_lshl_or_b32 v190, v4, 10, v2
	buffer_load_dwordx4 v190, s[4:7], 0 offen lds
	s_add_i32 m0, s3, 0x6000
	v_lshrrev_b32_e32 v0, 5, v176
	buffer_load_dwordx4 v184, s[8:11], 64 offen lds
	s_add_i32 m0, s3, 0x7000
	v_and_b32_e32 v1, 31, v176
	buffer_load_dwordx4 v185, s[8:11], 64 offen lds
	s_add_i32 m0, s3, 0x8000
	v_bfe_u32 v7, v176, 2, 2
	buffer_load_dwordx4 v186, s[8:11], 64 offen lds
	s_add_i32 m0, s3, 0x9000
	v_lshlrev_b32_e32 v5, 5, v1
	buffer_load_dwordx4 v187, s[8:11], 64 offen lds
	s_add_i32 m0, s3, 0xa000
	v_bitop3_b32 v0, v0, v7, 1 bitop3:0x6c
	buffer_load_dwordx4 v189, s[4:7], 64 offen lds
	s_add_i32 m0, s3, 0xb000
	v_lshl_or_b32 v6, s38, 12, v5
	buffer_load_dwordx4 v190, s[4:7], 64 offen lds
	s_add_i32 m0, s3, 0xc000
	v_lshlrev_b32_e32 v0, 3, v0
	buffer_load_dwordx4 v184, s[8:11], s35 offen lds
	s_add_i32 m0, s3, 0xd000
	s_and_b32 s18, s15, 1
	buffer_load_dwordx4 v185, s[8:11], s35 offen lds
	s_add_i32 m0, s3, 0xe000
	v_or_b32_e32 v193, v0, v6
	buffer_load_dwordx4 v186, s[8:11], s35 offen lds
	s_add_i32 m0, s3, 0xf000
	v_lshlrev_b32_e32 v181, 1, v193
	buffer_load_dwordx4 v187, s[8:11], s35 offen lds
	s_add_i32 m0, s3, 0x10000
	s_and_b32 s10, s14, 0x7ffff80
	buffer_load_dwordx4 v189, s[4:7], s35 offen lds
	s_add_i32 m0, s3, 0x11000
	v_or_b32_e32 v8, s10, v1
	buffer_load_dwordx4 v190, s[4:7], s35 offen lds
	v_lshlrev_b32_e32 v8, 5, v8
	v_or_b32_e32 v194, v8, v0
	v_lshl_or_b32 v5, s18, 11, v5
	v_lshl_or_b32 v179, s18, 6, v1
	s_waitcnt vmcnt(12)
	s_nop 0
	s_barrier
; #define MFMA32(a, b, c) __builtin_amdgcn_mfma_f32_32x32x16_bf16((a), (b), (c), 0, 0, 0)
; template <bool IN_PROJ>
; DI void gemm_tile(const Params& p, int layer, int nt, int tt, char* smem) {
;     ...
;   f32x16 acc[4][2];
; #pragma unroll
;   for (int a = 0; a < 4; ++a)
; #pragma unroll
;     for (int b = 0; b < 2; ++b)
; #pragma unroll
;       for (int i = 0; i < 16; ++i) acc[a][b][i] = 0.f;
;     ...
;   auto load_frags = [&](int kt, int ks, bf16x8 (&fa)[4], bf16x8 (&fb)[2]) {
;     const u16* sA = (const u16*)(smem + (kt % 3) * G_STAGE);
;     const u16* sB = sA + 8192;
; #pragma unroll
;     for (int fi = 0; fi < 4; ++fi) fa[fi] = *(const bf16x8*)(sA + gswz(wf * 128 + fi * 32 + r, ks * 2 + h));
; #pragma unroll
;     for (int ti = 0; ti < 2; ++ti) fb[ti] = *(const bf16x8*)(sB + gswz(wt * 64 + ti * 32 + r, ks * 2 + h));
;   };
;   auto mma = [&](const bf16x8 (&fa)[4], const bf16x8 (&fb)[2]) {
; #pragma unroll
;     for (int fi = 0; fi < 4; ++fi)
; #pragma unroll
;       for (int ti = 0; ti < 2; ++ti) acc[fi][ti] = MFMA32(fa[fi], fb[ti], acc[fi][ti]);
;   };
;   bf16x8 fa0[4], fb0[2], fa1[4], fb1[2];
;   asm volatile("s_waitcnt vmcnt(12)" ::: "memory");
;   __syncthreads();
;   load_frags(0, 0, fa0, fb0);
	v_lshlrev_b32_e32 v180, 1, v194
	ds_read_b128 v[148:151], v181
	ds_read_b128 v[144:147], v180 offset:2048
	ds_read_b128 v[136:139], v180 offset:4096
	ds_read_b128 v[128:131], v180 offset:6144
	v_or_b32_e32 v196, v5, v0
	v_lshlrev_b32_e32 v1, 5, v179
	v_lshlrev_b32_e32 v182, 1, v196
	v_or_b32_e32 v197, v1, v0
	v_lshlrev_b32_e32 v183, 1, v197
	ds_read_b128 v[140:143], v182 offset:16384
	ds_read_b128 v[132:135], v183 offset:18432
	v_bfe_u32 v178, v176, 5, 1
	v_bitop3_b32 v0, v178, v7, 2 bitop3:0x36
	v_lshlrev_b32_e32 v0, 3, v0
	v_mov_b32_e32 v64, 0
	s_and_b32 s17, s17, 0xffff
	s_mov_b32 s39, 0
	v_or_b32_e32 v192, v0, v6
	v_or_b32_e32 v191, v0, v5
	v_lshl_or_b32 v198, v3, 9, v2
	v_lshl_or_b32 v199, v4, 9, v2
	v_or_b32_e32 v195, v0, v8
	v_or_b32_e32 v188, v1, v0
	s_movk_i32 s40, 0xc0
	s_mov_b32 s10, s6
	v_mov_b32_e32 v65, v64
	v_mov_b32_e32 v66, v64
	v_mov_b32_e32 v67, v64
	v_mov_b32_e32 v68, v64
	v_mov_b32_e32 v69, v64
	v_mov_b32_e32 v70, v64
	v_mov_b32_e32 v71, v64
	v_mov_b32_e32 v72, v64
	v_mov_b32_e32 v73, v64
	v_mov_b32_e32 v74, v64
	v_mov_b32_e32 v75, v64
	v_mov_b32_e32 v76, v64
	v_mov_b32_e32 v77, v64
	v_mov_b32_e32 v78, v64
	v_mov_b32_e32 v79, v64
	v_mov_b32_e32 v112, v64
	v_mov_b32_e32 v113, v64
	v_mov_b32_e32 v114, v64
	v_mov_b32_e32 v115, v64
	v_mov_b32_e32 v116, v64
	v_mov_b32_e32 v117, v64
	v_mov_b32_e32 v118, v64
	v_mov_b32_e32 v119, v64
	v_mov_b32_e32 v120, v64
	v_mov_b32_e32 v121, v64
	v_mov_b32_e32 v122, v64
	v_mov_b32_e32 v123, v64
	v_mov_b32_e32 v124, v64
	v_mov_b32_e32 v125, v64
	v_mov_b32_e32 v126, v64
	v_mov_b32_e32 v127, v64
	v_mov_b32_e32 v96, v64
	v_mov_b32_e32 v97, v64
	v_mov_b32_e32 v98, v64
	v_mov_b32_e32 v99, v64
	v_mov_b32_e32 v100, v64
	v_mov_b32_e32 v101, v64
	v_mov_b32_e32 v102, v64
	v_mov_b32_e32 v103, v64
	v_mov_b32_e32 v104, v64
	v_mov_b32_e32 v105, v64
	v_mov_b32_e32 v106, v64
	v_mov_b32_e32 v107, v64
	v_mov_b32_e32 v108, v64
	v_mov_b32_e32 v109, v64
	v_mov_b32_e32 v110, v64
	v_mov_b32_e32 v111, v64
	v_mov_b32_e32 v80, v64
	v_mov_b32_e32 v81, v64
	v_mov_b32_e32 v82, v64
	v_mov_b32_e32 v83, v64
	v_mov_b32_e32 v84, v64
	v_mov_b32_e32 v85, v64
	v_mov_b32_e32 v86, v64
	v_mov_b32_e32 v87, v64
	v_mov_b32_e32 v88, v64
	v_mov_b32_e32 v89, v64
	v_mov_b32_e32 v90, v64
	v_mov_b32_e32 v91, v64
	v_mov_b32_e32 v92, v64
	v_mov_b32_e32 v93, v64
	v_mov_b32_e32 v94, v64
	v_mov_b32_e32 v95, v64
	v_mov_b32_e32 v48, v64
	v_mov_b32_e32 v49, v64
	v_mov_b32_e32 v50, v64
	v_mov_b32_e32 v51, v64
	v_mov_b32_e32 v52, v64
	v_mov_b32_e32 v53, v64
	v_mov_b32_e32 v54, v64
	v_mov_b32_e32 v55, v64
	v_mov_b32_e32 v56, v64
	v_mov_b32_e32 v57, v64
	v_mov_b32_e32 v58, v64
	v_mov_b32_e32 v59, v64
	v_mov_b32_e32 v60, v64
	v_mov_b32_e32 v61, v64
	v_mov_b32_e32 v62, v64
	v_mov_b32_e32 v63, v64
	v_mov_b32_e32 v32, v64
	v_mov_b32_e32 v33, v64
	v_mov_b32_e32 v34, v64
	v_mov_b32_e32 v35, v64
	v_mov_b32_e32 v36, v64
	v_mov_b32_e32 v37, v64
	v_mov_b32_e32 v38, v64
	v_mov_b32_e32 v39, v64
	v_mov_b32_e32 v40, v64
	v_mov_b32_e32 v41, v64
	v_mov_b32_e32 v42, v64
	v_mov_b32_e32 v43, v64
	v_mov_b32_e32 v44, v64
	v_mov_b32_e32 v45, v64
	v_mov_b32_e32 v46, v64
	v_mov_b32_e32 v47, v64
	v_mov_b32_e32 v16, v64
	v_mov_b32_e32 v17, v64
	v_mov_b32_e32 v18, v64
	v_mov_b32_e32 v19, v64
	v_mov_b32_e32 v20, v64
	v_mov_b32_e32 v21, v64
	v_mov_b32_e32 v22, v64
	v_mov_b32_e32 v23, v64
	v_mov_b32_e32 v24, v64
	v_mov_b32_e32 v25, v64
	v_mov_b32_e32 v26, v64
	v_mov_b32_e32 v27, v64
	v_mov_b32_e32 v28, v64
	v_mov_b32_e32 v29, v64
	v_mov_b32_e32 v30, v64
	v_mov_b32_e32 v31, v64
	v_mov_b32_e32 v0, v64
	v_mov_b32_e32 v1, v64
	v_mov_b32_e32 v2, v64
	v_mov_b32_e32 v3, v64
	v_mov_b32_e32 v4, v64
	v_mov_b32_e32 v5, v64
	v_mov_b32_e32 v6, v64
	v_mov_b32_e32 v7, v64
	v_mov_b32_e32 v8, v64
	v_mov_b32_e32 v9, v64
	v_mov_b32_e32 v10, v64
	v_mov_b32_e32 v11, v64
	v_mov_b32_e32 v12, v64
	v_mov_b32_e32 v13, v64
	v_mov_b32_e32 v14, v64
	v_mov_b32_e32 v15, v64
	s_branch .LBB0_731

; template <bool IN_PROJ>
; DI void gemm_tile(const Params& p, int layer, int nt, int tt, char* smem) {
;     ...
;   const __amdgpu_buffer_rsrc_t rA = __builtin_amdgcn_make_buffer_rsrc((void*)(Wt + (size_t)n0 * DM), 0, 0x7fffffff, 0x00020000);
;   const __amdgpu_buffer_rsrc_t rB0 = __builtin_amdgcn_make_buffer_rsrc((void*)(IN_PROJ ? xb + (size_t)t0 * DM : mixA + (size_t)t0 * 512), 0, 0x7fffffff, 0x00020000);
;   const __amdgpu_buffer_rsrc_t rB1 = __builtin_amdgcn_make_buffer_rsrc((void*)(mixB + (size_t)t0 * 256), 0, 0x7fffffff, 0x00020000);
;   const __amdgpu_buffer_rsrc_t rB2 = __builtin_amdgcn_make_buffer_rsrc((void*)(mixC + (size_t)t0 * 256), 0, 0x7fffffff, 0x00020000);
;   int voA[4], rowB[2], lcB[2];
; #pragma unroll
;   for (int i = 0; i < 4; ++i) { int c = tid + 256 * i; int row = c >> 2, lc = (c & 3) ^ ((row >> 2) & 3); voA[i] = row * (DM * 2) + lc * 16; }
; #pragma unroll
;   for (int i = 0; i < 2; ++i) { int c = tid + 256 * i; rowB[i] = c >> 2; lcB[i] = ((c & 3) ^ ((rowB[i] >> 2) & 3)) * 16; }
;   auto stage = [&](int kt) {
;     const int k0 = kt * 32;
;     char* base = smem + (kt % 3) * G_STAGE + w * 1024;
; #pragma unroll
;     for (int i = 0; i < 4; ++i)
;       __builtin_amdgcn_raw_ptr_buffer_load_lds(rA, (lds_ptr_t)(base + i * 4096), 16, voA[i], k0 * 2, 0, 0);
; #pragma unroll
;     for (int i = 0; i < 2; ++i) {
;       lds_ptr_t dst = (lds_ptr_t)(base + 16384 + i * 4096);
;       if (IN_PROJ) __builtin_amdgcn_raw_ptr_buffer_load_lds(rB0, dst, 16, rowB[i] * (DM * 2) + lcB[i], k0 * 2, 0, 0);
;       else {
;         if (k0 < 512) __builtin_amdgcn_raw_ptr_buffer_load_lds(rB0, dst, 16, rowB[i] * 1024 + lcB[i], k0 * 2, 0, 0);
;         else if (k0 < 768) __builtin_amdgcn_raw_ptr_buffer_load_lds(rB1, dst, 16, rowB[i] * 512 + lcB[i], (k0 - 512) * 2, 0, 0);
;         else __builtin_amdgcn_raw_ptr_buffer_load_lds(rB2, dst, 16, rowB[i] * 512 + lcB[i], (k0 - 768) * 2, 0, 0);
;       }
;     }
;   };
;   asm volatile("s_waitcnt vmcnt(0)" ::: "memory");
;   __syncthreads();
;   stage(0); stage(1); stage(2);
; template <bool IN_PROJ>
; DI void gemm_phase(const Params& p, int layer, char* smem) {
;     ...
;       __syncthreads();
;       if (tidx(p) == 0) *s_tile = (int)atomicAdd(ctr + xq, 1u);
;       __syncthreads();
;       const int q = __builtin_amdgcn_readfirstlane(*s_tile);
;       if (q >= PER_XCD) break;
;       int grp = q / (8 * NT), rem = q % (8 * NT);
.LBB0_789:
	s_or_b64 exec, exec, s[0:1]
	s_waitcnt lgkmcnt(0)
	s_barrier
	ds_read_b32 v0, v242
	s_mov_b64 s[0:1], -1
	s_waitcnt lgkmcnt(0)
	v_readfirstlane_b32 s2, v0
	s_cmpk_gt_i32 s2, 0x32f
	s_cbranch_scc1 .LBB0_784
	s_mul_hi_i32 s0, s2, 0x78787879
	s_lshr_b32 s1, s0, 31
	s_ashr_i32 s0, s0, 6
	s_add_i32 s1, s0, s1
	s_mul_i32 s0, s1, 0x88
	s_sub_i32 s2, s2, s0
	s_ashr_i32 s14, s2, 3
	s_lshl_b32 s2, s2, 3
	s_lshl_b32 s1, s1, 6
	s_and_b32 s2, s2, 56
	v_mov_b32_e32 v0, v234
	s_or_b32 s1, s2, s1
	s_lshl_b32 s12, s14, 8
	v_add_u32_e32 v247, s33, v0
	s_or_b32 s64, s1, s97
	s_ashr_i32 s13, s12, 31
	v_readfirstlane_b32 s15, v247
	s_ashr_i32 s1, s15, 6
	s_ashr_i32 s72, s15, 7
	s_lshl_b32 s92, s64, 7
	s_lshl_b64 s[2:3], s[12:13], 11
	s_add_u32 s4, s62, s2
	s_addc_u32 s5, s63, s3
	s_ashr_i32 s93, s92, 31
	s_lshl_b64 s[2:3], s[92:93], 11
	s_add_u32 s8, s48, s2
	v_lshlrev_b32_e32 v2, 4, v247
	s_addc_u32 s2, s49, s3
	v_lshlrev_b32_e32 v1, 9, v247
	v_bitop3_b32 v2, v2, 48, v247 bitop3:0x48
	s_and_b32 s3, s1, 1
	s_lshl_b32 s1, s1, 10
	v_and_or_b32 v181, v1, s80, v2
	s_and_b32 s5, s5, 0xffff
	s_mov_b32 m0, s1
	v_add_u32_e32 v182, 0x20000, v181
	s_waitcnt vmcnt(0)
	s_barrier
	buffer_load_dwordx4 v181, s[4:7], 0 offen lds
	s_add_i32 m0, s1, 0x1000
	v_add_u32_e32 v183, 0x40000, v181
	buffer_load_dwordx4 v182, s[4:7], 0 offen lds
	s_add_i32 m0, s1, 0x2000
	v_add_u32_e32 v184, 0x60000, v181
	v_add_u32_e32 v248, 0x100, v247
	buffer_load_dwordx4 v183, s[4:7], 0 offen lds
	s_add_i32 m0, s1, 0x3000
	s_and_b32 s9, s2, 0xffff
	s_mov_b32 s10, s6
	s_mov_b32 s11, s7
	buffer_load_dwordx4 v184, s[4:7], 0 offen lds
	s_add_i32 m0, s1, 0x4000
	v_lshlrev_b32_e32 v1, 9, v248
	buffer_load_dwordx4 v181, s[8:11], 0 offen lds
	s_add_i32 m0, s1, 0x5000
	v_and_or_b32 v185, v1, s80, v2
	buffer_load_dwordx4 v185, s[8:11], 0 offen lds
	s_add_i32 m0, s1, 0x6000
	v_lshrrev_b32_e32 v0, 5, v247
	buffer_load_dwordx4 v181, s[4:7], 64 offen lds
	s_add_i32 m0, s1, 0x7000
	v_and_b32_e32 v202, 31, v247
	buffer_load_dwordx4 v182, s[4:7], 64 offen lds
	s_add_i32 m0, s1, 0x8000
	v_bfe_u32 v3, v247, 2, 2
	buffer_load_dwordx4 v183, s[4:7], 64 offen lds
	s_add_i32 m0, s1, 0x9000
	v_lshlrev_b32_e32 v1, 5, v202
	buffer_load_dwordx4 v184, s[4:7], 64 offen lds
	s_add_i32 m0, s1, 0xa000
	v_bitop3_b32 v0, v0, v3, 1 bitop3:0x6c
	buffer_load_dwordx4 v181, s[8:11], 64 offen lds
	s_add_i32 m0, s1, 0xb000
	s_and_b32 s2, s15, 0x7ffff80
	buffer_load_dwordx4 v185, s[8:11], 64 offen lds
	s_add_i32 m0, s1, 0xc000
	v_lshl_or_b32 v2, s72, 12, v1
	buffer_load_dwordx4 v181, s[4:7], s81 offen lds
	s_add_i32 m0, s1, 0xd000
	v_lshlrev_b32_e32 v0, 3, v0
	buffer_load_dwordx4 v182, s[4:7], s81 offen lds
	s_add_i32 m0, s1, 0xe000
	v_or_b32_e32 v4, s2, v202
	buffer_load_dwordx4 v183, s[4:7], s81 offen lds
	s_add_i32 m0, s1, 0xf000
	v_or_b32_e32 v189, v0, v2
	buffer_load_dwordx4 v184, s[4:7], s81 offen lds
	s_add_i32 m0, s1, 0x10000
	v_lshlrev_b32_e32 v4, 5, v4
	buffer_load_dwordx4 v181, s[8:11], s81 offen lds
	s_add_i32 m0, s1, 0x11000
	s_lshl_b32 s65, s3, 6
	buffer_load_dwordx4 v185, s[8:11], s81 offen lds
	v_lshlrev_b32_e32 v177, 1, v189
	v_or_b32_e32 v190, v4, v0
	v_lshl_or_b32 v1, s3, 11, v1
	v_or_b32_e32 v200, s65, v202
	v_readlane_b32 s98, v249, 10
	v_readlane_b32 s99, v249, 11
	v_or_b32_e32 v206, s92, v200
	v_ashrrev_i32_e32 v207, 31, v206
	v_lshl_add_u64 v[206:207], v[206:207], 2, s[98:99]
	global_load_dword v204, v[206:207], off
	global_load_dword v205, v[206:207], off offset:128
	s_waitcnt vmcnt(12)
	s_nop 0
	s_barrier
; #define MFMA32(a, b, c) __builtin_amdgcn_mfma_f32_32x32x16_bf16((a), (b), (c), 0, 0, 0)
; template <bool IN_PROJ>
; DI void gemm_tile(const Params& p, int layer, int nt, int tt, char* smem) {
;     ...
;   f32x16 acc[4][2];
; #pragma unroll
;   for (int a = 0; a < 4; ++a)
; #pragma unroll
;     for (int b = 0; b < 2; ++b)
; #pragma unroll
;       for (int i = 0; i < 16; ++i) acc[a][b][i] = 0.f;
;     ...
;   auto load_frags = [&](int kt, int ks, bf16x8 (&fa)[4], bf16x8 (&fb)[2]) {
;     const u16* sA = (const u16*)(smem + (kt % 3) * G_STAGE);
;     const u16* sB = sA + 8192;
; #pragma unroll
;     for (int fi = 0; fi < 4; ++fi) fa[fi] = *(const bf16x8*)(sA + gswz(wf * 128 + fi * 32 + r, ks * 2 + h));
; #pragma unroll
;     for (int ti = 0; ti < 2; ++ti) fb[ti] = *(const bf16x8*)(sB + gswz(wt * 64 + ti * 32 + r, ks * 2 + h));
;   };
;   auto mma = [&](const bf16x8 (&fa)[4], const bf16x8 (&fb)[2]) {
; #pragma unroll
;     for (int fi = 0; fi < 4; ++fi)
; #pragma unroll
;       for (int ti = 0; ti < 2; ++ti) acc[fi][ti] = MFMA32(fa[fi], fb[ti], acc[fi][ti]);
;   };
;   bf16x8 fa0[4], fb0[2], fa1[4], fb1[2];
;   asm volatile("s_waitcnt vmcnt(12)" ::: "memory");
;   __syncthreads();
;   load_frags(0, 0, fa0, fb0);
	v_lshlrev_b32_e32 v176, 1, v190
	ds_read_b128 v[132:135], v177
	ds_read_b128 v[104:107], v176 offset:2048
	ds_read_b128 v[100:103], v176 offset:4096
	ds_read_b128 v[96:99], v176 offset:6144
	v_or_b32_e32 v191, v1, v0
	v_lshlrev_b32_e32 v5, 5, v200
	v_lshlrev_b32_e32 v178, 1, v191
	v_or_b32_e32 v192, v5, v0
	v_lshlrev_b32_e32 v179, 1, v192
	ds_read_b128 v[128:131], v178 offset:16384
	ds_read_b128 v[108:111], v179 offset:18432
	v_bfe_u32 v201, v247, 5, 1
	v_bitop3_b32 v0, v201, v3, 2 bitop3:0x36
	v_lshlrev_b32_e32 v0, 3, v0
	v_mov_b32_e32 v64, 0
	s_mov_b32 s0, 3
	v_or_b32_e32 v188, v0, v2
	v_or_b32_e32 v187, v0, v1
	v_or_b32_e32 v186, v0, v4
	v_or_b32_e32 v180, v5, v0
	s_movk_i32 s2, 0xc0
	v_mov_b32_e32 v65, v64
	v_mov_b32_e32 v66, v64
	v_mov_b32_e32 v67, v64
	v_mov_b32_e32 v68, v64
	v_mov_b32_e32 v69, v64
	v_mov_b32_e32 v70, v64
	v_mov_b32_e32 v71, v64
	v_mov_b32_e32 v72, v64
	v_mov_b32_e32 v73, v64
	v_mov_b32_e32 v74, v64
	v_mov_b32_e32 v75, v64
	v_mov_b32_e32 v76, v64
	v_mov_b32_e32 v77, v64
	v_mov_b32_e32 v78, v64
	v_mov_b32_e32 v79, v64
	v_mov_b32_e32 v0, v64
	v_mov_b32_e32 v1, v64
	v_mov_b32_e32 v2, v64
	v_mov_b32_e32 v3, v64
	v_mov_b32_e32 v4, v64
	v_mov_b32_e32 v5, v64
	v_mov_b32_e32 v6, v64
	v_mov_b32_e32 v7, v64
	v_mov_b32_e32 v8, v64
	v_mov_b32_e32 v9, v64
	v_mov_b32_e32 v10, v64
	v_mov_b32_e32 v11, v64
	v_mov_b32_e32 v12, v64
	v_mov_b32_e32 v13, v64
	v_mov_b32_e32 v14, v64
	v_mov_b32_e32 v15, v64
	v_mov_b32_e32 v80, v64
	v_mov_b32_e32 v81, v64
	v_mov_b32_e32 v82, v64
	v_mov_b32_e32 v83, v64
	v_mov_b32_e32 v84, v64
	v_mov_b32_e32 v85, v64
	v_mov_b32_e32 v86, v64
	v_mov_b32_e32 v87, v64
	v_mov_b32_e32 v88, v64
	v_mov_b32_e32 v89, v64
	v_mov_b32_e32 v90, v64
	v_mov_b32_e32 v91, v64
	v_mov_b32_e32 v92, v64
	v_mov_b32_e32 v93, v64
	v_mov_b32_e32 v94, v64
	v_mov_b32_e32 v95, v64
	v_mov_b32_e32 v16, v64
	v_mov_b32_e32 v17, v64
	v_mov_b32_e32 v18, v64
	v_mov_b32_e32 v19, v64
	v_mov_b32_e32 v20, v64
	v_mov_b32_e32 v21, v64
	v_mov_b32_e32 v22, v64
	v_mov_b32_e32 v23, v64
	v_mov_b32_e32 v24, v64
	v_mov_b32_e32 v25, v64
	v_mov_b32_e32 v26, v64
	v_mov_b32_e32 v27, v64
	v_mov_b32_e32 v28, v64
	v_mov_b32_e32 v29, v64
	v_mov_b32_e32 v30, v64
	v_mov_b32_e32 v31, v64
	v_mov_b32_e32 v112, v64
	v_mov_b32_e32 v113, v64
	v_mov_b32_e32 v114, v64
	v_mov_b32_e32 v115, v64
	v_mov_b32_e32 v116, v64
	v_mov_b32_e32 v117, v64
	v_mov_b32_e32 v118, v64
	v_mov_b32_e32 v119, v64
	v_mov_b32_e32 v120, v64
	v_mov_b32_e32 v121, v64
	v_mov_b32_e32 v122, v64
	v_mov_b32_e32 v123, v64
	v_mov_b32_e32 v124, v64
	v_mov_b32_e32 v125, v64
	v_mov_b32_e32 v126, v64
	v_mov_b32_e32 v127, v64
	v_mov_b32_e32 v32, v64
	v_mov_b32_e32 v33, v64
	v_mov_b32_e32 v34, v64
	v_mov_b32_e32 v35, v64
	v_mov_b32_e32 v36, v64
	v_mov_b32_e32 v37, v64
	v_mov_b32_e32 v38, v64
	v_mov_b32_e32 v39, v64
	v_mov_b32_e32 v40, v64
	v_mov_b32_e32 v41, v64
	v_mov_b32_e32 v42, v64
	v_mov_b32_e32 v43, v64
	v_mov_b32_e32 v44, v64
	v_mov_b32_e32 v45, v64
	v_mov_b32_e32 v46, v64
	v_mov_b32_e32 v47, v64
	v_mov_b32_e32 v144, v64
	v_mov_b32_e32 v145, v64
	v_mov_b32_e32 v146, v64
	v_mov_b32_e32 v147, v64
	v_mov_b32_e32 v148, v64
	v_mov_b32_e32 v149, v64
	v_mov_b32_e32 v150, v64
	v_mov_b32_e32 v151, v64
	v_mov_b32_e32 v152, v64
	v_mov_b32_e32 v153, v64
	v_mov_b32_e32 v154, v64
	v_mov_b32_e32 v155, v64
	v_mov_b32_e32 v156, v64
	v_mov_b32_e32 v157, v64
	v_mov_b32_e32 v158, v64
	v_mov_b32_e32 v159, v64
	v_mov_b32_e32 v48, v64
	v_mov_b32_e32 v49, v64
	v_mov_b32_e32 v50, v64
	v_mov_b32_e32 v51, v64
	v_mov_b32_e32 v52, v64
	v_mov_b32_e32 v53, v64
	v_mov_b32_e32 v54, v64
	v_mov_b32_e32 v55, v64
	v_mov_b32_e32 v56, v64
	v_mov_b32_e32 v57, v64
	v_mov_b32_e32 v58, v64
	v_mov_b32_e32 v59, v64
	v_mov_b32_e32 v60, v64
	v_mov_b32_e32 v61, v64
	v_mov_b32_e32 v62, v64
	v_mov_b32_e32 v63, v64
